# grid barrier: XCD last arriver publishes the XCD generation word before its own acquire invalidate (waiters acquire for themselves)
# baseline (speedup 1.0000x reference)
; DI unsigned xb_ld(unsigned* p) { return __hip_atomic_load(p, __ATOMIC_RELAXED, __HIP_MEMORY_SCOPE_AGENT); }
; DI unsigned xb_add(unsigned* p, unsigned v) { return __hip_atomic_fetch_add(p, v, __ATOMIC_RELAXED, __HIP_MEMORY_SCOPE_AGENT); }
; #define XB_SPIN(cond, bar) do { unsigned _sp = 0; while (cond) { __builtin_amdgcn_s_sleep(1); \
;     if ((++_sp & 255u) == 0u) { if (xb_ld(&(bar)[XB_TMO])) break; if (_sp > XB_SPIN_CAP) { atomicAdd(&(bar)[XB_TMO], 1u); break; } } } } while (0)
; DI void xcd_barrier(XcdBarrier& b) {
;     ...
;     if (old + 1u == (gen + 1u) * nloc) {
;       __builtin_amdgcn_fence(__ATOMIC_RELEASE, "agent");
;       asm volatile("s_waitcnt vmcnt(0)" ::: "memory");
;       const unsigned og = xb_add(&bar[XB_TOP], 1u);
;       const unsigned tg = og / nx;
;       if (og + 1u == (tg + 1u) * nx) xb_add(&bar[XB_TOPGEN], 1u);
;       else XB_SPIN(xb_ld(&bar[XB_TOPGEN]) == tg, bar);
;       __builtin_amdgcn_fence(__ATOMIC_ACQUIRE, "agent");
;       xb_add(&bar[XB_XGEN(b.x)], 1u);
;       asm volatile("s_waitcnt vmcnt(0)" ::: "memory");
.LBB0_128:
	s_or_b64 exec, exec, s[38:39]
	s_waitcnt vmcnt(0)
	global_atomic_add v[112:113], v133, off
	buffer_inv sc1
	s_waitcnt vmcnt(0)
